# same as previous but LayerNorm wave_sum left as the compiler's ds_bpermute butterflies (A/B of the DPP replacement in LN only)
# speedup vs baseline: 1.0059x; 1.0011x over previous
; __device__ __forceinline__ float wave_sum(float v) {
; #pragma unroll
;   for (int o = 32; o >= 1; o >>= 1) v += __shfl_xor(v, o);
;   return v;
; }
; __device__ __forceinline__ void ln_finish_row(int r, int lane, f32x4 (&x)[8], float* dstf, bf16_t* dstb, const float* g, const float* bta) {
;   float sm = 0.f;
; #pragma unroll
;   for (int k = 0; k < 8; ++k) sm += x[k][0] + x[k][1] + x[k][2] + x[k][3];
;   const float mean = wave_sum(sm) * (1.0f / 2048.0f);
;   float q = 0.f;
; #pragma unroll
;   for (int k = 0; k < 8; ++k) { x[k] = x[k] - mean; q += x[k][0] * x[k][0] + x[k][1] * x[k][1] + x[k][2] * x[k][2] + x[k][3] * x[k][3]; }
;   const float rstd = rsqrtf(wave_sum(q) * (1.0f / 2048.0f) + LN_EPS);
.LBB0_158:
	s_or_b64 exec, exec, s[48:49]
	s_waitcnt vmcnt(0)
	v_add_f32_e32 v67, v24, v25
	v_add_f32_e32 v67, v26, v67
	v_add_f32_e32 v103, v32, v33
	v_add_f32_e32 v67, v27, v67
	v_add_f32_e32 v103, v34, v103
	v_add_f32_e32 v67, 0, v67
	v_add_f32_e32 v103, v35, v103
	v_add_f32_e32 v67, v67, v103
	v_add_f32_e32 v103, v36, v37
	v_add_f32_e32 v103, v38, v103
	v_add_f32_e32 v103, v39, v103
	v_add_f32_e32 v67, v67, v103
	v_add_f32_e32 v103, v44, v45
	v_mov_b32_e32 v116, v48
	v_mov_b32_e32 v117, v52
	v_mov_b32_e32 v118, v49
	v_mov_b32_e32 v119, v53
	v_add_f32_e32 v103, v46, v103
	v_pk_add_f32 v[116:117], v[116:117], v[118:119]
	v_mov_b32_e32 v118, v50
	v_mov_b32_e32 v119, v54
	v_add_f32_e32 v103, v47, v103
	v_pk_add_f32 v[116:117], v[118:119], v[116:117]
	v_mov_b32_e32 v118, v51
	v_mov_b32_e32 v119, v55
	v_add_f32_e32 v67, v67, v103
	v_pk_add_f32 v[116:117], v[118:119], v[116:117]
	v_mov_b32_e32 v118, v57
	v_add_f32_e32 v67, v67, v116
	v_add_f32_e32 v67, v67, v117
	v_mov_b32_e32 v116, v56
	v_mov_b32_e32 v117, v60
	v_mov_b32_e32 v119, v61
	v_pk_add_f32 v[116:117], v[116:117], v[118:119]
	v_mov_b32_e32 v118, v58
	v_mov_b32_e32 v119, v62
	v_pk_add_f32 v[116:117], v[118:119], v[116:117]
	v_mov_b32_e32 v118, v59
	v_mov_b32_e32 v119, v63
	v_pk_add_f32 v[116:117], v[118:119], v[116:117]
	s_nop 1
	v_mov_b64_e32 v[130:131], v[164:165]
	v_mov_b64_e32 v[132:133], v[166:167]
	s_nop 1
	v_mov_b64_e32 v[134:135], v[170:171]
	v_mov_b64_e32 v[136:137], v[172:173]
	v_add_f32_e32 v67, v67, v116
	v_add_f32_e32 v67, v67, v117
	ds_bpermute_b32 v103, v69, v67
	s_mov_b32 s29, 0x800000
	s_waitcnt lgkmcnt(0)
	v_add_f32_e32 v67, v67, v103
	ds_bpermute_b32 v103, v124, v67
	s_waitcnt lgkmcnt(0)
	v_add_f32_e32 v67, v67, v103
	ds_bpermute_b32 v103, v125, v67
	s_waitcnt lgkmcnt(0)
	v_add_f32_e32 v67, v67, v103
	ds_bpermute_b32 v103, v126, v67
	s_waitcnt lgkmcnt(0)
	v_add_f32_e32 v67, v67, v103
	ds_bpermute_b32 v103, v127, v67
	s_waitcnt lgkmcnt(0)
	v_add_f32_e32 v67, v67, v103
	ds_bpermute_b32 v103, v128, v67
	s_waitcnt lgkmcnt(0)
	v_add_f32_e32 v67, v67, v103
	v_fmac_f32_e32 v25, 0xba000000, v67
	v_fmac_f32_e32 v33, 0xba000000, v67
	v_fmamk_f32 v123, v67, 0xba000000, v27
	v_fmamk_f32 v122, v67, 0xba000000, v26
	v_fmamk_f32 v24, v67, 0xba000000, v24
	v_mul_f32_e32 v26, v25, v25
	v_fmamk_f32 v32, v67, 0xba000000, v32
	v_mul_f32_e32 v27, v33, v33
	v_fmac_f32_e32 v26, v24, v24
	v_fmamk_f32 v120, v67, 0xba000000, v34
	v_fmac_f32_e32 v27, v32, v32
	v_fmac_f32_e32 v26, v122, v122
	v_fmamk_f32 v121, v67, 0xba000000, v35
	v_fmac_f32_e32 v27, v120, v120
	v_fmac_f32_e32 v26, v123, v123
	v_fmac_f32_e32 v27, v121, v121
	v_fmac_f32_e32 v37, 0xba000000, v67
	v_add_f32_e32 v26, v26, v27
	v_fmamk_f32 v36, v67, 0xba000000, v36
	v_mul_f32_e32 v27, v37, v37
	v_fmamk_f32 v118, v67, 0xba000000, v38
	v_fmac_f32_e32 v27, v36, v36
	v_fmamk_f32 v119, v67, 0xba000000, v39
	v_fmac_f32_e32 v27, v118, v118
	v_fmac_f32_e32 v27, v119, v119
	v_fmac_f32_e32 v45, 0xba000000, v67
	v_add_f32_e32 v26, v27, v26
	v_fmamk_f32 v44, v67, 0xba000000, v44
	v_mul_f32_e32 v27, v45, v45
	v_fmamk_f32 v116, v67, 0xba000000, v46
	v_fmac_f32_e32 v27, v44, v44
	v_fmamk_f32 v117, v67, 0xba000000, v47
	v_fmac_f32_e32 v27, v116, v116
	v_fmamk_f32 v49, v67, 0xba000000, v49
	v_fmamk_f32 v53, v67, 0xba000000, v53
	v_fmac_f32_e32 v27, v117, v117
	v_fmac_f32_e32 v48, 0xba000000, v67
	v_fmac_f32_e32 v52, 0xba000000, v67
	v_mov_b32_e32 v38, v53
	v_mov_b32_e32 v39, v49
	v_add_f32_e32 v46, v27, v26
	v_fmamk_f32 v50, v67, 0xba000000, v50
	v_fmamk_f32 v34, v67, 0xba000000, v54
	v_mov_b32_e32 v26, v52
	v_mov_b32_e32 v27, v48
	v_pk_mul_f32 v[38:39], v[38:39], v[38:39]
	v_fmamk_f32 v51, v67, 0xba000000, v51
	v_fmamk_f32 v35, v67, 0xba000000, v55
	v_pk_fma_f32 v[26:27], v[26:27], v[26:27], v[38:39]
	v_mov_b32_e32 v38, v34
	v_mov_b32_e32 v39, v50
	v_pk_fma_f32 v[26:27], v[38:39], v[38:39], v[26:27]
	v_mov_b32_e32 v38, v35
	v_mov_b32_e32 v39, v51
	v_pk_fma_f32 v[26:27], v[38:39], v[38:39], v[26:27]
	v_fmamk_f32 v57, v67, 0xba000000, v57
	v_fmamk_f32 v61, v67, 0xba000000, v61
	v_add_f32_e32 v27, v27, v46
	v_fmac_f32_e32 v56, 0xba000000, v67
	v_fmac_f32_e32 v60, 0xba000000, v67
	v_mov_b32_e32 v54, v61
	v_mov_b32_e32 v55, v57
	v_add_f32_e32 v103, v26, v27
	v_fmamk_f32 v38, v67, 0xba000000, v58
	v_fmamk_f32 v26, v67, 0xba000000, v62
	v_mov_b32_e32 v46, v60
	v_mov_b32_e32 v47, v56
	v_pk_mul_f32 v[54:55], v[54:55], v[54:55]
	v_fmamk_f32 v39, v67, 0xba000000, v59
	v_fmamk_f32 v27, v67, 0xba000000, v63
	v_pk_fma_f32 v[46:47], v[46:47], v[46:47], v[54:55]
	v_mov_b32_e32 v54, v26
	v_mov_b32_e32 v55, v38
	v_pk_fma_f32 v[46:47], v[54:55], v[54:55], v[46:47]
	v_mov_b32_e32 v54, v27
	v_mov_b32_e32 v55, v39
	v_pk_fma_f32 v[46:47], v[54:55], v[54:55], v[46:47]
	s_nop 0
	v_add_f32_e32 v47, v47, v103
	v_add_f32_e32 v46, v46, v47
	ds_bpermute_b32 v47, v69, v46
	s_waitcnt lgkmcnt(0)
	v_add_f32_e32 v46, v46, v47
	ds_bpermute_b32 v47, v124, v46
	s_waitcnt lgkmcnt(0)
	v_add_f32_e32 v46, v46, v47
	ds_bpermute_b32 v47, v125, v46
	s_waitcnt lgkmcnt(0)
	v_add_f32_e32 v46, v46, v47
	ds_bpermute_b32 v47, v126, v46
	s_waitcnt lgkmcnt(0)
	v_add_f32_e32 v46, v46, v47
	ds_bpermute_b32 v47, v127, v46
	s_waitcnt lgkmcnt(0)
	v_add_f32_e32 v46, v46, v47
	ds_bpermute_b32 v47, v128, v46
	s_waitcnt lgkmcnt(0)
; __device__ __forceinline__ u32x2 pack4(f32x4 v) { u32x2 r; r[0] = cvt_pk(v[0], v[1]); r[1] = cvt_pk(v[2], v[3]); return r; }
; __device__ __forceinline__ void ln_finish_row(int r, int lane, f32x4 (&x)[8], float* dstf, bf16_t* dstb, const float* g, const float* bta) {
;     ...
;   const float rstd = rsqrtf(wave_sum(q) * (1.0f / 2048.0f) + LN_EPS);
; #pragma unroll
;   for (int k = 0; k < 8; ++k) {
;     const int col = 256 * k + 4 * lane;
;     const f32x4 gg = *(const f32x4*)(g + col), bb = *(const f32x4*)(bta + col);
;     const f32x4 y = x[k] * rstd * gg + bb;
;     *(f32x4*)(dstf + (size_t)r * 2048 + col) = y;
;     if (dstb) *(u32x2*)(dstb + (size_t)r * 2048 + col) = pack4(y);
;   }
	v_add_f32_e32 v46, v46, v47
	v_fmamk_f32 v46, v46, 0x3a000000, v228
	v_cmp_gt_f32_e32 vcc, s29, v46
	v_mul_f32_e32 v47, 0x4b800000, v46
	s_mov_b32 s29, 0x19f09000
	v_cndmask_b32_e32 v46, v46, v47, vcc
	v_rsq_f32_e32 v46, v46
	s_nop 0
	v_mul_f32_e32 v47, 0x45800000, v46
	v_cndmask_b32_e32 v46, v46, v47, vcc
	v_pk_mul_f32 v[54:55], v[122:123], v[46:47] op_sel_hi:[1,0]
	v_pk_mul_f32 v[24:25], v[24:25], v[46:47] op_sel_hi:[1,0]
	v_pk_fma_f32 v[132:133], v[132:133], v[54:55], v[136:137]
	v_lshl_add_u64 v[54:55], s[24:25], 0, v[96:97]
	v_pk_fma_f32 v[130:131], v[130:131], v[24:25], v[134:135]
	v_add_co_u32_e32 v54, vcc, s29, v54
	v_cvt_pk_bf16_f32 v24, v130, v131
	v_cvt_pk_bf16_f32 v25, v132, v133
	v_addc_co_u32_e32 v55, vcc, 0, v55, vcc
	global_store_dwordx4 v[112:113], v[130:133], off
	global_store_dwordx2 v[54:55], v[24:25], off
	s_nop 1
	v_mov_b64_e32 v[130:131], v[174:175]
	v_mov_b64_e32 v[132:133], v[176:177]
	s_nop 0
	s_nop 1
	v_mov_b64_e32 v[134:135], v[178:179]
	v_mov_b64_e32 v[136:137], v[180:181]
	v_pk_mul_f32 v[24:25], v[120:121], v[46:47] op_sel_hi:[1,0]
	v_pk_mul_f32 v[32:33], v[32:33], v[46:47] op_sel_hi:[1,0]
	s_mov_b32 s29, 0x109000
	v_pk_mul_f32 v[36:37], v[36:37], v[46:47] op_sel_hi:[1,0]
	v_pk_mul_f32 v[26:27], v[26:27], v[46:47] op_sel_hi:[1,0]
	v_pk_fma_f32 v[120:121], v[130:131], v[32:33], v[134:135]
	v_pk_fma_f32 v[122:123], v[132:133], v[24:25], v[136:137]
	v_add_co_u32_e32 v24, vcc, s29, v110
	v_cvt_pk_bf16_f32 v32, v120, v121
	s_nop 0
	v_addc_co_u32_e32 v25, vcc, 0, v111, vcc
	v_cvt_pk_bf16_f32 v33, v122, v123
	global_store_dwordx4 v[24:25], v[120:123], off offset:1024
	global_store_dwordx2 v[54:55], v[32:33], off offset:512
	s_nop 1
	v_mov_b64_e32 v[120:121], v[182:183]
	v_mov_b64_e32 v[122:123], v[184:185]
	s_nop 0
	s_nop 1
	v_mov_b64_e32 v[130:131], v[188:189]
	v_mov_b64_e32 v[132:133], v[190:191]
	v_pk_mul_f32 v[32:33], v[118:119], v[46:47] op_sel_hi:[1,0]
	s_mov_b32 s29, 0x10a000
	v_pk_fma_f32 v[118:119], v[120:121], v[36:37], v[130:131]
	v_pk_fma_f32 v[120:121], v[122:123], v[32:33], v[132:133]
	v_cvt_pk_bf16_f32 v32, v118, v119
	v_cvt_pk_bf16_f32 v33, v120, v121
	global_store_dwordx4 v[24:25], v[118:121], off offset:2048
	global_store_dwordx2 v[54:55], v[32:33], off offset:1024
	s_nop 1
	v_mov_b64_e32 v[118:119], v[192:193]
	v_mov_b64_e32 v[120:121], v[194:195]
	s_nop 0
	s_nop 1
	v_mov_b64_e32 v[130:131], v[196:197]
	v_mov_b64_e32 v[132:133], v[198:199]
	v_pk_mul_f32 v[32:33], v[116:117], v[46:47] op_sel_hi:[1,0]
	v_pk_mul_f32 v[36:37], v[44:45], v[46:47] op_sel_hi:[1,0]
	v_add_co_u32_e32 v44, vcc, s29, v110
	v_pk_fma_f32 v[116:117], v[118:119], v[36:37], v[130:131]
	v_pk_fma_f32 v[118:119], v[120:121], v[32:33], v[132:133]
	global_store_dwordx4 v[24:25], v[116:119], off offset:3072
	v_cvt_pk_bf16_f32 v24, v116, v117
	v_cvt_pk_bf16_f32 v25, v118, v119
	global_store_dwordx2 v[54:55], v[24:25], off offset:1536
	s_nop 1
	v_mov_b64_e32 v[116:117], v[200:201]
	v_mov_b64_e32 v[118:119], v[202:203]
	s_nop 1
	v_mov_b64_e32 v[120:121], v[204:205]
	v_mov_b64_e32 v[122:123], v[206:207]
	v_pk_mul_f32 v[24:25], v[50:51], v[46:47] op_sel_hi:[1,0]
	v_pk_mul_f32 v[32:33], v[48:49], v[46:47] op_sel_hi:[1,0]
	v_addc_co_u32_e32 v45, vcc, 0, v111, vcc
	v_pk_mul_f32 v[36:37], v[56:57], v[46:47] op_sel_hi:[1,0]
	v_pk_fma_f32 v[48:49], v[116:117], v[32:33], v[120:121]
	v_pk_fma_f32 v[50:51], v[118:119], v[24:25], v[122:123]
	v_cvt_pk_bf16_f32 v24, v48, v49
	v_cvt_pk_bf16_f32 v25, v50, v51
	global_store_dwordx4 v[44:45], v[48:51], off
	global_store_dwordx2 v[54:55], v[24:25], off offset:2048
	s_nop 1
	v_mov_b64_e32 v[48:49], v[208:209]
	v_mov_b64_e32 v[50:51], v[210:211]
	s_nop 0
	s_nop 1
	v_mov_b64_e32 v[110:111], v[212:213]
	v_mov_b64_e32 v[112:113], v[214:215]
	v_pk_mul_f32 v[24:25], v[34:35], v[46:47] op_sel_hi:[1,0]
	v_pk_mul_f32 v[32:33], v[52:53], v[46:47] op_sel_hi:[1,0]
	v_pk_fma_f32 v[34:35], v[50:51], v[24:25], v[112:113]
	v_pk_fma_f32 v[32:33], v[48:49], v[32:33], v[110:111]
	v_cvt_pk_bf16_f32 v25, v34, v35
	v_cvt_pk_bf16_f32 v24, v32, v33
	global_store_dwordx4 v[44:45], v[32:35], off offset:1024
	global_store_dwordx2 v[54:55], v[24:25], off offset:2560
	s_nop 1
	v_mov_b64_e32 v[32:33], v[216:217]
	v_mov_b64_e32 v[34:35], v[218:219]
	s_nop 0
	s_nop 1
	v_mov_b64_e32 v[48:49], v[220:221]
	v_mov_b64_e32 v[50:51], v[222:223]
	v_pk_mul_f32 v[24:25], v[38:39], v[46:47] op_sel_hi:[1,0]
	v_pk_fma_f32 v[32:33], v[32:33], v[36:37], v[48:49]
	v_pk_fma_f32 v[34:35], v[34:35], v[24:25], v[50:51]
	v_cvt_pk_bf16_f32 v24, v32, v33
	v_cvt_pk_bf16_f32 v25, v34, v35
	global_store_dwordx4 v[44:45], v[32:35], off offset:2048
	global_store_dwordx2 v[54:55], v[24:25], off offset:3072
	s_nop 1
	v_mov_b64_e32 v[32:33], v[238:239]
	v_mov_b64_e32 v[34:35], v[240:241]
	s_nop 0
	s_nop 1
	v_mov_b64_e32 v[36:37], v[242:243]
	v_mov_b64_e32 v[38:39], v[244:245]
	v_pk_mul_f32 v[24:25], v[60:61], v[46:47] op_sel_hi:[1,0]
	v_pk_fma_f32 v[26:27], v[26:27], v[34:35], v[38:39]
	v_pk_fma_f32 v[24:25], v[24:25], v[32:33], v[36:37]
	global_store_dwordx4 v[44:45], v[24:27], off offset:3072
	s_nop 1
	v_cvt_pk_bf16_f32 v24, v24, v25
	v_cvt_pk_bf16_f32 v25, v26, v27
	global_store_dwordx2 v[54:55], v[24:25], off offset:3584
	s_and_saveexec_b64 s[38:39], s[36:37]
	s_cbranch_execz .LBB0_91
; __device__ __forceinline__ float wave_sum(float v) {
; #pragma unroll
;   for (int o = 32; o >= 1; o >>= 1) v += __shfl_xor(v, o);
;   return v;
; }
; __device__ __forceinline__ void ln_finish_row(int r, int lane, f32x4 (&x)[8], float* dstf, bf16_t* dstb, const float* g, const float* bta) {
;   float sm = 0.f;
; #pragma unroll
;   for (int k = 0; k < 8; ++k) sm += x[k][0] + x[k][1] + x[k][2] + x[k][3];
;   const float mean = wave_sum(sm) * (1.0f / 2048.0f);
;   float q = 0.f;
; #pragma unroll
;   for (int k = 0; k < 8; ++k) { x[k] = x[k] - mean; q += x[k][0] * x[k][0] + x[k][1] * x[k][1] + x[k][2] * x[k][2] + x[k][3] * x[k][3]; }
;   const float rstd = rsqrtf(wave_sum(q) * (1.0f / 2048.0f) + LN_EPS);
	v_add_f32_e32 v24, v0, v1
	v_add_f32_e32 v24, v2, v24
	v_add_f32_e32 v25, v4, v5
	v_add_f32_e32 v24, v3, v24
	v_add_f32_e32 v25, v6, v25
	v_add_f32_e32 v24, 0, v24
	v_add_f32_e32 v25, v7, v25
	v_add_f32_e32 v24, v25, v24
	v_add_f32_e32 v25, v8, v9
	v_add_f32_e32 v25, v10, v25
	v_add_f32_e32 v25, v11, v25
	v_add_f32_e32 v24, v25, v24
	v_add_f32_e32 v25, v12, v13
	v_add_f32_e32 v25, v14, v25
	v_add_f32_e32 v25, v15, v25
	v_add_f32_e32 v32, v25, v24
	v_mov_b32_e32 v24, v20
	v_mov_b32_e32 v25, v16
	v_mov_b32_e32 v26, v21
	v_mov_b32_e32 v27, v17
	v_pk_add_f32 v[24:25], v[24:25], v[26:27]
	v_mov_b32_e32 v26, v22
	v_mov_b32_e32 v27, v18
	v_pk_add_f32 v[24:25], v[26:27], v[24:25]
	v_mov_b32_e32 v26, v23
	v_mov_b32_e32 v27, v19
	v_pk_add_f32 v[24:25], v[26:27], v[24:25]
	v_mov_b32_e32 v26, v41
	v_add_f32_e32 v25, v25, v32
	v_add_f32_e32 v32, v24, v25
	v_mov_b32_e32 v24, v40
	v_mov_b32_e32 v25, v28
	v_mov_b32_e32 v27, v29
	v_pk_add_f32 v[24:25], v[24:25], v[26:27]
	v_mov_b32_e32 v26, v42
	v_mov_b32_e32 v27, v30
	v_pk_add_f32 v[24:25], v[26:27], v[24:25]
	v_mov_b32_e32 v26, v43
	v_mov_b32_e32 v27, v31
	v_pk_add_f32 v[24:25], v[26:27], v[24:25]
	s_mov_b32 s29, 0x800000
	v_add_f32_e32 v25, v25, v32
	v_add_f32_e32 v24, v24, v25
	ds_bpermute_b32 v25, v69, v24
	v_readlane_b32 s34, v254, 30
	v_readlane_b32 s35, v254, 31
	v_mov_b32_e32 v103, v65
	v_mov_b32_e32 v105, v65
	s_waitcnt lgkmcnt(0)
	v_add_f32_e32 v24, v24, v25
	ds_bpermute_b32 v25, v124, v24
	v_mov_b32_e32 v107, v65
	v_mov_b32_e32 v109, v65
	s_waitcnt lgkmcnt(0)
	v_add_f32_e32 v24, v24, v25
	ds_bpermute_b32 v25, v125, v24
	s_waitcnt lgkmcnt(0)
	v_add_f32_e32 v24, v24, v25
	ds_bpermute_b32 v25, v126, v24
	s_waitcnt lgkmcnt(0)
	v_add_f32_e32 v24, v24, v25
	ds_bpermute_b32 v25, v127, v24
	s_waitcnt lgkmcnt(0)
	v_add_f32_e32 v24, v24, v25
	ds_bpermute_b32 v25, v128, v24
	s_waitcnt lgkmcnt(0)
	v_add_f32_e32 v44, v24, v25
	v_fmamk_f32 v1, v44, 0xba000000, v1
	v_fmamk_f32 v5, v44, 0xba000000, v5
	v_fmac_f32_e32 v0, 0xba000000, v44
	v_mul_f32_e32 v24, v1, v1
	v_fmac_f32_e32 v4, 0xba000000, v44
	v_mul_f32_e32 v25, v5, v5
	v_fmamk_f32 v2, v44, 0xba000000, v2
	v_fmac_f32_e32 v24, v0, v0
	v_fmamk_f32 v6, v44, 0xba000000, v6
	v_fmac_f32_e32 v25, v4, v4
	v_fmamk_f32 v3, v44, 0xba000000, v3
	v_fmac_f32_e32 v24, v2, v2
	v_fmamk_f32 v7, v44, 0xba000000, v7
	v_fmac_f32_e32 v25, v6, v6
	v_fmac_f32_e32 v24, v3, v3
	v_fmac_f32_e32 v25, v7, v7
	v_fmamk_f32 v9, v44, 0xba000000, v9
	v_add_f32_e32 v24, v24, v25
	v_fmac_f32_e32 v8, 0xba000000, v44
	v_mul_f32_e32 v25, v9, v9
	v_fmamk_f32 v10, v44, 0xba000000, v10
	v_fmac_f32_e32 v25, v8, v8
	v_fmamk_f32 v11, v44, 0xba000000, v11
	v_fmac_f32_e32 v25, v10, v10
	v_fmac_f32_e32 v25, v11, v11
	v_fmamk_f32 v13, v44, 0xba000000, v13
	v_add_f32_e32 v24, v25, v24
	v_fmac_f32_e32 v12, 0xba000000, v44
	v_mul_f32_e32 v25, v13, v13
	v_fmamk_f32 v14, v44, 0xba000000, v14
	v_fmac_f32_e32 v25, v12, v12
	v_fmamk_f32 v15, v44, 0xba000000, v15
	v_fmac_f32_e32 v25, v14, v14
	v_fmamk_f32 v17, v44, 0xba000000, v17
	v_fmamk_f32 v21, v44, 0xba000000, v21
	v_fmac_f32_e32 v25, v15, v15
	v_fmac_f32_e32 v16, 0xba000000, v44
	v_fmac_f32_e32 v20, 0xba000000, v44
	v_mov_b32_e32 v26, v21
	v_mov_b32_e32 v27, v17
	v_add_f32_e32 v45, v25, v24
	v_mov_b32_e32 v24, v20
	v_mov_b32_e32 v25, v16
	v_pk_mul_f32 v[26:27], v[26:27], v[26:27]
	v_fmamk_f32 v18, v44, 0xba000000, v18
	v_pk_fma_f32 v[36:37], v[24:25], v[24:25], v[26:27]
	s_nop 1
	v_mov_b64_e32 v[24:25], v[164:165]
	v_mov_b64_e32 v[26:27], v[166:167]
	s_nop 1
	v_mov_b64_e32 v[32:33], v[170:171]
	v_mov_b64_e32 v[34:35], v[172:173]
	v_fmamk_f32 v22, v44, 0xba000000, v22
	v_fmamk_f32 v19, v44, 0xba000000, v19
	v_fmamk_f32 v23, v44, 0xba000000, v23
	v_mov_b32_e32 v38, v22
	v_mov_b32_e32 v39, v18
	v_pk_fma_f32 v[36:37], v[38:39], v[38:39], v[36:37]
	v_mov_b32_e32 v38, v23
	v_mov_b32_e32 v39, v19
	v_pk_fma_f32 v[36:37], v[38:39], v[38:39], v[36:37]
	v_fmamk_f32 v29, v44, 0xba000000, v29
	v_fmamk_f32 v41, v44, 0xba000000, v41
	v_add_f32_e32 v37, v37, v45
	v_fmac_f32_e32 v28, 0xba000000, v44
	v_fmac_f32_e32 v40, 0xba000000, v44
	v_mov_b32_e32 v38, v41
	v_mov_b32_e32 v39, v29
	v_add_f32_e32 v45, v36, v37
	v_fmamk_f32 v30, v44, 0xba000000, v30
	v_fmamk_f32 v42, v44, 0xba000000, v42
	v_mov_b32_e32 v36, v40
	v_mov_b32_e32 v37, v28
	v_pk_mul_f32 v[38:39], v[38:39], v[38:39]
	v_fmamk_f32 v31, v44, 0xba000000, v31
	v_fmamk_f32 v43, v44, 0xba000000, v43
	v_pk_fma_f32 v[36:37], v[36:37], v[36:37], v[38:39]
	v_mov_b32_e32 v38, v42
	v_mov_b32_e32 v39, v30
	v_pk_fma_f32 v[36:37], v[38:39], v[38:39], v[36:37]
	v_mov_b32_e32 v38, v43
	v_mov_b32_e32 v39, v31
	v_pk_fma_f32 v[36:37], v[38:39], v[38:39], v[36:37]
	v_lshlrev_b64 v[38:39], 13, v[114:115]
	v_add_f32_e32 v37, v37, v45
	v_add_f32_e32 v36, v36, v37
	ds_bpermute_b32 v37, v69, v36
	v_lshl_add_u64 v[38:39], s[34:35], 0, v[38:39]
	s_waitcnt lgkmcnt(0)
	v_add_f32_e32 v36, v36, v37
	ds_bpermute_b32 v37, v124, v36
	s_waitcnt lgkmcnt(0)
	v_add_f32_e32 v36, v36, v37
	ds_bpermute_b32 v37, v125, v36
	s_waitcnt lgkmcnt(0)
	v_add_f32_e32 v36, v36, v37
	ds_bpermute_b32 v37, v126, v36
	s_waitcnt lgkmcnt(0)
; __device__ __forceinline__ u32x2 pack4(f32x4 v) { u32x2 r; r[0] = cvt_pk(v[0], v[1]); r[1] = cvt_pk(v[2], v[3]); return r; }
; __device__ __forceinline__ void ln_finish_row(int r, int lane, f32x4 (&x)[8], float* dstf, bf16_t* dstb, const float* g, const float* bta) {
;     ...
;   const float rstd = rsqrtf(wave_sum(q) * (1.0f / 2048.0f) + LN_EPS);
; #pragma unroll
;   for (int k = 0; k < 8; ++k) {
;     const int col = 256 * k + 4 * lane;
;     const f32x4 gg = *(const f32x4*)(g + col), bb = *(const f32x4*)(bta + col);
;     const f32x4 y = x[k] * rstd * gg + bb;
;     *(f32x4*)(dstf + (size_t)r * 2048 + col) = y;
;     if (dstb) *(u32x2*)(dstb + (size_t)r * 2048 + col) = pack4(y);
;   }
	v_add_f32_e32 v36, v36, v37
	ds_bpermute_b32 v37, v127, v36
	s_waitcnt lgkmcnt(0)
	v_add_f32_e32 v36, v36, v37
	ds_bpermute_b32 v37, v128, v36
	s_waitcnt lgkmcnt(0)
	v_add_f32_e32 v36, v36, v37
	v_fmamk_f32 v36, v36, 0x3a000000, v228
	v_mul_f32_e32 v37, 0x4b800000, v36
	v_cmp_gt_f32_e32 vcc, s29, v36
	s_nop 1
	v_cndmask_b32_e32 v36, v36, v37, vcc
	v_rsq_f32_e32 v36, v36
	s_nop 0
	v_mul_f32_e32 v37, 0x45800000, v36
	v_cndmask_b32_e32 v36, v36, v37, vcc
	v_pk_mul_f32 v[44:45], v[0:1], v[36:37] op_sel_hi:[1,0]
	v_pk_mul_f32 v[46:47], v[2:3], v[36:37] op_sel_hi:[1,0]
	v_pk_fma_f32 v[24:25], v[24:25], v[44:45], v[32:33]
	v_pk_fma_f32 v[26:27], v[26:27], v[46:47], v[34:35]
	v_lshl_add_u64 v[44:45], v[38:39], 0, v[64:65]
	global_store_dwordx4 v[44:45], v[24:27], off
	v_pk_mul_f32 v[48:49], v[6:7], v[36:37] op_sel_hi:[1,0]
	v_pk_mul_f32 v[50:51], v[4:5], v[36:37] op_sel_hi:[1,0]
	v_cvt_pk_bf16_f32 v24, v24, v25
	v_cvt_pk_bf16_f32 v25, v26, v27
	v_lshlrev_b64 v[26:27], 12, v[114:115]
	v_lshl_add_u64 v[46:47], v[94:95], 0, v[26:27]
	global_store_dwordx2 v[46:47], v[24:25], off
	s_nop 1
	v_mov_b64_e32 v[24:25], v[174:175]
	v_mov_b64_e32 v[26:27], v[176:177]
	s_nop 0
	s_nop 1
	v_mov_b64_e32 v[32:33], v[178:179]
	v_mov_b64_e32 v[34:35], v[180:181]
	v_pk_fma_f32 v[24:25], v[24:25], v[50:51], v[32:33]
	v_pk_fma_f32 v[26:27], v[26:27], v[48:49], v[34:35]
	global_store_dwordx4 v[44:45], v[24:27], off offset:1024
	v_pk_mul_f32 v[48:49], v[10:11], v[36:37] op_sel_hi:[1,0]
	v_pk_mul_f32 v[50:51], v[8:9], v[36:37] op_sel_hi:[1,0]
	v_cvt_pk_bf16_f32 v24, v24, v25
	v_cvt_pk_bf16_f32 v25, v26, v27
	global_store_dwordx2 v[46:47], v[24:25], off offset:512
	s_nop 1
	v_mov_b64_e32 v[24:25], v[182:183]
	v_mov_b64_e32 v[26:27], v[184:185]
	s_nop 0
	s_nop 1
	v_mov_b64_e32 v[32:33], v[188:189]
	v_mov_b64_e32 v[34:35], v[190:191]
	v_pk_fma_f32 v[24:25], v[24:25], v[50:51], v[32:33]
	v_pk_fma_f32 v[26:27], v[26:27], v[48:49], v[34:35]
	global_store_dwordx4 v[44:45], v[24:27], off offset:2048
	v_pk_mul_f32 v[48:49], v[14:15], v[36:37] op_sel_hi:[1,0]
	v_pk_mul_f32 v[50:51], v[12:13], v[36:37] op_sel_hi:[1,0]
	v_cvt_pk_bf16_f32 v24, v24, v25
	v_cvt_pk_bf16_f32 v25, v26, v27
	global_store_dwordx2 v[46:47], v[24:25], off offset:1024
	s_nop 1
	v_mov_b64_e32 v[24:25], v[192:193]
	v_mov_b64_e32 v[26:27], v[194:195]
	s_nop 0
	s_nop 1
	v_mov_b64_e32 v[32:33], v[196:197]
	v_mov_b64_e32 v[34:35], v[198:199]
	v_pk_fma_f32 v[24:25], v[24:25], v[50:51], v[32:33]
	v_pk_fma_f32 v[26:27], v[26:27], v[48:49], v[34:35]
	global_store_dwordx4 v[44:45], v[24:27], off offset:3072
	v_pk_mul_f32 v[48:49], v[18:19], v[36:37] op_sel_hi:[1,0]
	v_pk_mul_f32 v[50:51], v[16:17], v[36:37] op_sel_hi:[1,0]
	v_cvt_pk_bf16_f32 v24, v24, v25
	v_cvt_pk_bf16_f32 v25, v26, v27
	global_store_dwordx2 v[46:47], v[24:25], off offset:1536
	s_nop 1
	v_mov_b64_e32 v[24:25], v[200:201]
	v_mov_b64_e32 v[26:27], v[202:203]
	s_nop 0
	s_nop 1
	v_mov_b64_e32 v[32:33], v[204:205]
	v_mov_b64_e32 v[34:35], v[206:207]
	v_lshl_add_u64 v[44:45], v[38:39], 0, v[102:103]
	v_pk_fma_f32 v[24:25], v[24:25], v[50:51], v[32:33]
	v_pk_fma_f32 v[26:27], v[26:27], v[48:49], v[34:35]
	global_store_dwordx4 v[44:45], v[24:27], off
	v_pk_mul_f32 v[48:49], v[22:23], v[36:37] op_sel_hi:[1,0]
	v_pk_mul_f32 v[50:51], v[20:21], v[36:37] op_sel_hi:[1,0]
	v_cvt_pk_bf16_f32 v24, v24, v25
	v_cvt_pk_bf16_f32 v25, v26, v27
	global_store_dwordx2 v[46:47], v[24:25], off offset:2048
	s_nop 1
	v_mov_b64_e32 v[24:25], v[208:209]
	v_mov_b64_e32 v[26:27], v[210:211]
	s_nop 0
	s_nop 1
	v_mov_b64_e32 v[32:33], v[212:213]
	v_mov_b64_e32 v[34:35], v[214:215]
	v_lshl_add_u64 v[44:45], v[38:39], 0, v[104:105]
	v_pk_fma_f32 v[24:25], v[24:25], v[50:51], v[32:33]
	v_pk_fma_f32 v[26:27], v[26:27], v[48:49], v[34:35]
	global_store_dwordx4 v[44:45], v[24:27], off
	v_pk_mul_f32 v[48:49], v[30:31], v[36:37] op_sel_hi:[1,0]
	v_pk_mul_f32 v[50:51], v[28:29], v[36:37] op_sel_hi:[1,0]
	v_cvt_pk_bf16_f32 v24, v24, v25
	v_cvt_pk_bf16_f32 v25, v26, v27
	global_store_dwordx2 v[46:47], v[24:25], off offset:2560
	s_nop 1
	v_mov_b64_e32 v[24:25], v[216:217]
	v_mov_b64_e32 v[26:27], v[218:219]
	s_nop 0
	s_nop 1
	v_mov_b64_e32 v[32:33], v[220:221]
	v_mov_b64_e32 v[34:35], v[222:223]
	v_lshl_add_u64 v[44:45], v[38:39], 0, v[106:107]
	v_lshl_add_u64 v[38:39], v[38:39], 0, v[108:109]
	v_pk_fma_f32 v[24:25], v[24:25], v[50:51], v[32:33]
	v_pk_fma_f32 v[26:27], v[26:27], v[48:49], v[34:35]
	global_store_dwordx4 v[44:45], v[24:27], off
	v_pk_mul_f32 v[44:45], v[42:43], v[36:37] op_sel_hi:[1,0]
	v_pk_mul_f32 v[36:37], v[40:41], v[36:37] op_sel_hi:[1,0]
	v_cvt_pk_bf16_f32 v24, v24, v25
	v_cvt_pk_bf16_f32 v25, v26, v27
	global_store_dwordx2 v[46:47], v[24:25], off offset:3072
	s_nop 1
	v_mov_b64_e32 v[24:25], v[238:239]
	v_mov_b64_e32 v[26:27], v[240:241]
	s_nop 0
	s_nop 1
	v_mov_b64_e32 v[32:33], v[242:243]
	v_mov_b64_e32 v[34:35], v[244:245]
	v_pk_fma_f32 v[24:25], v[36:37], v[24:25], v[32:33]
	v_pk_fma_f32 v[26:27], v[44:45], v[26:27], v[34:35]
	global_store_dwordx4 v[38:39], v[24:27], off
	s_nop 1
	v_cvt_pk_bf16_f32 v24, v24, v25
	v_cvt_pk_bf16_f32 v25, v26, v27
	global_store_dwordx2 v[46:47], v[24:25], off offset:3584
	s_branch .LBB0_91

; __device__ __forceinline__ float wave_sum(float v) {
; #pragma unroll
;   for (int o = 32; o >= 1; o >>= 1) v += __shfl_xor(v, o);
;   return v;
; }
; __device__ __forceinline__ void ln_finish_row(int r, int lane, f32x4 (&x)[8], float* dstf, bf16_t* dstb, const float* g, const float* bta) {
;   float sm = 0.f;
; #pragma unroll
;   for (int k = 0; k < 8; ++k) sm += x[k][0] + x[k][1] + x[k][2] + x[k][3];
;   const float mean = wave_sum(sm) * (1.0f / 2048.0f);
;   float q = 0.f;
; #pragma unroll
;   for (int k = 0; k < 8; ++k) { x[k] = x[k] - mean; q += x[k][0] * x[k][0] + x[k][1] * x[k][1] + x[k][2] * x[k][2] + x[k][3] * x[k][3]; }
;   const float rstd = rsqrtf(wave_sum(q) * (1.0f / 2048.0f) + LN_EPS);
.LBB0_1561:
	s_or_b64 exec, exec, s[42:43]
	s_waitcnt vmcnt(0)
	v_add_f32_e32 v64, v20, v21
	v_add_f32_e32 v64, v22, v64
	v_add_f32_e32 v67, v28, v29
	v_add_f32_e32 v64, v23, v64
	v_add_f32_e32 v67, v30, v67
	v_add_f32_e32 v64, 0, v64
	v_add_f32_e32 v67, v31, v67
	v_add_f32_e32 v64, v64, v67
	v_add_f32_e32 v67, v36, v37
	v_add_f32_e32 v67, v38, v67
	v_add_f32_e32 v67, v39, v67
	v_add_f32_e32 v64, v64, v67
	v_add_f32_e32 v67, v44, v45
	v_mov_b32_e32 v112, v48
	v_mov_b32_e32 v113, v52
	v_mov_b32_e32 v114, v49
	v_mov_b32_e32 v115, v53
	v_add_f32_e32 v67, v46, v67
	v_pk_add_f32 v[112:113], v[112:113], v[114:115]
	v_mov_b32_e32 v114, v50
	v_mov_b32_e32 v115, v54
	v_add_f32_e32 v67, v47, v67
	v_pk_add_f32 v[112:113], v[114:115], v[112:113]
	v_mov_b32_e32 v114, v51
	v_mov_b32_e32 v115, v55
	v_add_f32_e32 v64, v64, v67
	v_pk_add_f32 v[112:113], v[114:115], v[112:113]
	v_mov_b32_e32 v114, v57
	v_add_f32_e32 v64, v64, v112
	v_add_f32_e32 v64, v64, v113
	v_mov_b32_e32 v112, v56
	v_mov_b32_e32 v113, v60
	v_mov_b32_e32 v115, v61
	v_pk_add_f32 v[112:113], v[112:113], v[114:115]
	v_mov_b32_e32 v114, v58
	v_mov_b32_e32 v115, v62
	v_pk_add_f32 v[112:113], v[114:115], v[112:113]
	v_mov_b32_e32 v114, v59
	v_mov_b32_e32 v115, v63
	v_pk_add_f32 v[112:113], v[114:115], v[112:113]
	s_nop 1
	v_mov_b64_e32 v[128:129], v[160:161]
	v_mov_b64_e32 v[130:131], v[162:163]
	s_nop 1
	v_mov_b64_e32 v[132:133], v[164:165]
	v_mov_b64_e32 v[134:135], v[166:167]
	v_add_f32_e32 v64, v64, v112
	v_add_f32_e32 v64, v64, v113
	ds_bpermute_b32 v67, v120, v64
	s_mov_b32 s29, 0x800000
	s_waitcnt lgkmcnt(0)
	v_add_f32_e32 v64, v64, v67
	ds_bpermute_b32 v67, v121, v64
	s_waitcnt lgkmcnt(0)
	v_add_f32_e32 v64, v64, v67
	ds_bpermute_b32 v67, v122, v64
	s_waitcnt lgkmcnt(0)
	v_add_f32_e32 v64, v64, v67
	ds_bpermute_b32 v67, v123, v64
	s_waitcnt lgkmcnt(0)
	v_add_f32_e32 v64, v64, v67
	ds_bpermute_b32 v67, v124, v64
	s_waitcnt lgkmcnt(0)
	v_add_f32_e32 v64, v64, v67
	ds_bpermute_b32 v67, v125, v64
	s_waitcnt lgkmcnt(0)
	v_add_f32_e32 v64, v64, v67
	v_fmac_f32_e32 v21, 0xba000000, v64
	v_fmac_f32_e32 v29, 0xba000000, v64
	v_fmamk_f32 v119, v64, 0xba000000, v23
	v_fmamk_f32 v118, v64, 0xba000000, v22
	v_fmamk_f32 v20, v64, 0xba000000, v20
	v_mul_f32_e32 v22, v21, v21
	v_fmamk_f32 v28, v64, 0xba000000, v28
	v_mul_f32_e32 v23, v29, v29
	v_fmac_f32_e32 v22, v20, v20
	v_fmamk_f32 v116, v64, 0xba000000, v30
	v_fmac_f32_e32 v23, v28, v28
	v_fmac_f32_e32 v22, v118, v118
	v_fmamk_f32 v117, v64, 0xba000000, v31
	v_fmac_f32_e32 v23, v116, v116
	v_fmac_f32_e32 v22, v119, v119
	v_fmac_f32_e32 v23, v117, v117
	v_fmac_f32_e32 v37, 0xba000000, v64
	v_add_f32_e32 v22, v22, v23
	v_fmamk_f32 v36, v64, 0xba000000, v36
	v_mul_f32_e32 v23, v37, v37
	v_fmamk_f32 v114, v64, 0xba000000, v38
	v_fmac_f32_e32 v23, v36, v36
	v_fmamk_f32 v115, v64, 0xba000000, v39
	v_fmac_f32_e32 v23, v114, v114
	v_fmac_f32_e32 v23, v115, v115
	v_fmac_f32_e32 v45, 0xba000000, v64
	v_add_f32_e32 v22, v23, v22
	v_fmamk_f32 v44, v64, 0xba000000, v44
	v_mul_f32_e32 v23, v45, v45
	v_fmamk_f32 v112, v64, 0xba000000, v46
	v_fmac_f32_e32 v23, v44, v44
	v_fmamk_f32 v113, v64, 0xba000000, v47
	v_fmac_f32_e32 v23, v112, v112
	v_fmamk_f32 v49, v64, 0xba000000, v49
	v_fmamk_f32 v53, v64, 0xba000000, v53
	v_fmac_f32_e32 v23, v113, v113
	v_fmac_f32_e32 v48, 0xba000000, v64
	v_fmac_f32_e32 v52, 0xba000000, v64
	v_mov_b32_e32 v38, v53
	v_mov_b32_e32 v39, v49
	v_add_f32_e32 v46, v23, v22
	v_fmamk_f32 v50, v64, 0xba000000, v50
	v_fmamk_f32 v30, v64, 0xba000000, v54
	v_mov_b32_e32 v22, v52
	v_mov_b32_e32 v23, v48
	v_pk_mul_f32 v[38:39], v[38:39], v[38:39]
	v_fmamk_f32 v51, v64, 0xba000000, v51
	v_fmamk_f32 v31, v64, 0xba000000, v55
	v_pk_fma_f32 v[22:23], v[22:23], v[22:23], v[38:39]
	v_mov_b32_e32 v38, v30
	v_mov_b32_e32 v39, v50
	v_pk_fma_f32 v[22:23], v[38:39], v[38:39], v[22:23]
	v_mov_b32_e32 v38, v31
	v_mov_b32_e32 v39, v51
	v_pk_fma_f32 v[22:23], v[38:39], v[38:39], v[22:23]
	v_fmamk_f32 v57, v64, 0xba000000, v57
	v_fmamk_f32 v61, v64, 0xba000000, v61
	v_add_f32_e32 v23, v23, v46
	v_fmac_f32_e32 v56, 0xba000000, v64
	v_fmac_f32_e32 v60, 0xba000000, v64
	v_mov_b32_e32 v54, v61
	v_mov_b32_e32 v55, v57
	v_add_f32_e32 v67, v22, v23
	v_fmamk_f32 v38, v64, 0xba000000, v58
	v_fmamk_f32 v22, v64, 0xba000000, v62
	v_mov_b32_e32 v46, v60
	v_mov_b32_e32 v47, v56
	v_pk_mul_f32 v[54:55], v[54:55], v[54:55]
	v_fmamk_f32 v39, v64, 0xba000000, v59
	v_fmamk_f32 v23, v64, 0xba000000, v63
	v_pk_fma_f32 v[46:47], v[46:47], v[46:47], v[54:55]
	v_mov_b32_e32 v54, v22
	v_mov_b32_e32 v55, v38
	v_pk_fma_f32 v[46:47], v[54:55], v[54:55], v[46:47]
	v_mov_b32_e32 v54, v23
	v_mov_b32_e32 v55, v39
	v_pk_fma_f32 v[46:47], v[54:55], v[54:55], v[46:47]
	s_nop 0
	v_add_f32_e32 v47, v47, v67
	v_add_f32_e32 v46, v46, v47
	ds_bpermute_b32 v47, v120, v46
	s_waitcnt lgkmcnt(0)
	v_add_f32_e32 v46, v46, v47
	ds_bpermute_b32 v47, v121, v46
	s_waitcnt lgkmcnt(0)
	v_add_f32_e32 v46, v46, v47
	ds_bpermute_b32 v47, v122, v46
	s_waitcnt lgkmcnt(0)
	v_add_f32_e32 v46, v46, v47
	ds_bpermute_b32 v47, v123, v46
	s_waitcnt lgkmcnt(0)
	v_add_f32_e32 v46, v46, v47
	ds_bpermute_b32 v47, v124, v46
	s_waitcnt lgkmcnt(0)
	v_add_f32_e32 v46, v46, v47
	ds_bpermute_b32 v47, v125, v46
	s_waitcnt lgkmcnt(0)
; __device__ __forceinline__ u32x2 pack4(f32x4 v) { u32x2 r; r[0] = cvt_pk(v[0], v[1]); r[1] = cvt_pk(v[2], v[3]); return r; }
; __device__ __forceinline__ void ln_finish_row(int r, int lane, f32x4 (&x)[8], float* dstf, bf16_t* dstb, const float* g, const float* bta) {
;   float sm = 0.f;
; #pragma unroll
;   for (int k = 0; k < 8; ++k) sm += x[k][0] + x[k][1] + x[k][2] + x[k][3];
;   const float mean = wave_sum(sm) * (1.0f / 2048.0f);
;     ...
;   const float rstd = rsqrtf(wave_sum(q) * (1.0f / 2048.0f) + LN_EPS);
; #pragma unroll
;   for (int k = 0; k < 8; ++k) {
;     const int col = 256 * k + 4 * lane;
;     const f32x4 gg = *(const f32x4*)(g + col), bb = *(const f32x4*)(bta + col);
;     const f32x4 y = x[k] * rstd * gg + bb;
;     *(f32x4*)(dstf + (size_t)r * 2048 + col) = y;
;     if (dstb) *(u32x2*)(dstb + (size_t)r * 2048 + col) = pack4(y);
;   }
	v_add_f32_e32 v46, v46, v47
	v_fmamk_f32 v46, v46, 0x3a000000, v228
	v_cmp_gt_f32_e32 vcc, s29, v46
	v_mul_f32_e32 v47, 0x4b800000, v46
	s_movk_i32 s29, 0x1000
	v_cndmask_b32_e32 v46, v46, v47, vcc
	v_rsq_f32_e32 v46, v46
	s_nop 0
	v_mul_f32_e32 v47, 0x45800000, v46
	v_cndmask_b32_e32 v46, v46, v47, vcc
	v_pk_mul_f32 v[20:21], v[20:21], v[46:47] op_sel_hi:[1,0]
	v_pk_mul_f32 v[54:55], v[118:119], v[46:47] op_sel_hi:[1,0]
	v_pk_fma_f32 v[128:129], v[128:129], v[20:21], v[132:133]
	v_pk_fma_f32 v[130:131], v[130:131], v[54:55], v[134:135]
	v_lshl_add_u64 v[20:21], v[98:99], 0, v[94:95]
	global_store_dwordx4 v[20:21], v[128:131], off
	s_nop 1
	v_mov_b64_e32 v[128:129], v[170:171]
	v_mov_b64_e32 v[130:131], v[172:173]
	s_nop 0
	s_nop 1
	v_mov_b64_e32 v[132:133], v[174:175]
	v_mov_b64_e32 v[134:135], v[176:177]
	v_pk_mul_f32 v[54:55], v[116:117], v[46:47] op_sel_hi:[1,0]
	v_pk_mul_f32 v[28:29], v[28:29], v[46:47] op_sel_hi:[1,0]
	v_pk_mul_f32 v[36:37], v[36:37], v[46:47] op_sel_hi:[1,0]
	v_pk_mul_f32 v[22:23], v[22:23], v[46:47] op_sel_hi:[1,0]
	v_pk_fma_f32 v[116:117], v[128:129], v[28:29], v[132:133]
	v_pk_fma_f32 v[118:119], v[130:131], v[54:55], v[134:135]
	global_store_dwordx4 v[20:21], v[116:119], off offset:1024
	s_nop 1
	v_mov_b64_e32 v[116:117], v[178:179]
	v_mov_b64_e32 v[118:119], v[180:181]
	s_nop 0
	s_nop 1
	v_mov_b64_e32 v[128:129], v[182:183]
	v_mov_b64_e32 v[130:131], v[184:185]
	v_pk_mul_f32 v[28:29], v[114:115], v[46:47] op_sel_hi:[1,0]
	v_pk_fma_f32 v[114:115], v[116:117], v[36:37], v[128:129]
	v_pk_fma_f32 v[116:117], v[118:119], v[28:29], v[130:131]
	global_store_dwordx4 v[20:21], v[114:117], off offset:2048
	s_nop 1
	v_mov_b64_e32 v[114:115], v[188:189]
	v_mov_b64_e32 v[116:117], v[190:191]
	s_nop 0
	s_nop 1
	v_mov_b64_e32 v[128:129], v[192:193]
	v_mov_b64_e32 v[130:131], v[194:195]
	v_pk_mul_f32 v[28:29], v[112:113], v[46:47] op_sel_hi:[1,0]
	v_pk_mul_f32 v[36:37], v[44:45], v[46:47] op_sel_hi:[1,0]
	v_add_co_u32_e32 v44, vcc, s29, v20
	v_pk_fma_f32 v[112:113], v[114:115], v[36:37], v[128:129]
	v_pk_fma_f32 v[114:115], v[116:117], v[28:29], v[130:131]
	global_store_dwordx4 v[20:21], v[112:115], off offset:3072
	s_nop 1
	v_mov_b64_e32 v[112:113], v[196:197]
	v_mov_b64_e32 v[114:115], v[198:199]
	s_nop 0
	s_nop 1
	v_mov_b64_e32 v[116:117], v[200:201]
	v_mov_b64_e32 v[118:119], v[202:203]
	v_pk_mul_f32 v[28:29], v[50:51], v[46:47] op_sel_hi:[1,0]
	v_pk_mul_f32 v[36:37], v[48:49], v[46:47] op_sel_hi:[1,0]
	v_addc_co_u32_e32 v45, vcc, 0, v21, vcc
	v_pk_mul_f32 v[20:21], v[30:31], v[46:47] op_sel_hi:[1,0]
	v_pk_fma_f32 v[48:49], v[112:113], v[36:37], v[116:117]
	v_pk_fma_f32 v[50:51], v[114:115], v[28:29], v[118:119]
	global_store_dwordx4 v[44:45], v[48:51], off
	s_nop 1
	v_mov_b64_e32 v[48:49], v[204:205]
	v_mov_b64_e32 v[50:51], v[206:207]
	s_nop 0
	s_nop 1
	v_mov_b64_e32 v[112:113], v[208:209]
	v_mov_b64_e32 v[114:115], v[210:211]
	v_pk_mul_f32 v[28:29], v[52:53], v[46:47] op_sel_hi:[1,0]
	v_pk_mul_f32 v[36:37], v[56:57], v[46:47] op_sel_hi:[1,0]
	v_pk_fma_f32 v[28:29], v[48:49], v[28:29], v[112:113]
	v_pk_fma_f32 v[30:31], v[50:51], v[20:21], v[114:115]
	global_store_dwordx4 v[44:45], v[28:31], off offset:1024
	s_nop 1
	v_mov_b64_e32 v[28:29], v[212:213]
	v_mov_b64_e32 v[30:31], v[214:215]
	s_nop 0
	s_nop 1
	v_mov_b64_e32 v[48:49], v[216:217]
	v_mov_b64_e32 v[50:51], v[218:219]
	v_pk_mul_f32 v[20:21], v[38:39], v[46:47] op_sel_hi:[1,0]
	v_pk_fma_f32 v[28:29], v[28:29], v[36:37], v[48:49]
	v_pk_fma_f32 v[30:31], v[30:31], v[20:21], v[50:51]
	global_store_dwordx4 v[44:45], v[28:31], off offset:2048
	s_nop 1
	v_mov_b64_e32 v[28:29], v[220:221]
	v_mov_b64_e32 v[30:31], v[222:223]
	s_nop 0
	s_nop 1
	v_mov_b64_e32 v[36:37], v[238:239]
	v_mov_b64_e32 v[38:39], v[240:241]
	v_pk_mul_f32 v[20:21], v[60:61], v[46:47] op_sel_hi:[1,0]
	v_pk_fma_f32 v[22:23], v[30:31], v[22:23], v[38:39]
	v_pk_fma_f32 v[20:21], v[28:29], v[20:21], v[36:37]
	global_store_dwordx4 v[44:45], v[20:23], off offset:3072
	s_and_saveexec_b64 s[42:43], s[36:37]
	s_cbranch_execz .LBB0_1494
	v_add_f32_e32 v20, v0, v1
	v_add_f32_e32 v20, v2, v20
	v_add_f32_e32 v21, v4, v5
	v_add_f32_e32 v20, v3, v20
	v_add_f32_e32 v21, v6, v21
	v_add_f32_e32 v20, 0, v20
	v_add_f32_e32 v21, v7, v21
	v_add_f32_e32 v20, v21, v20
	v_add_f32_e32 v21, v8, v9
	v_add_f32_e32 v21, v10, v21
	v_add_f32_e32 v21, v11, v21
	v_add_f32_e32 v20, v21, v20
	v_add_f32_e32 v21, v12, v13
	v_add_f32_e32 v21, v14, v21
	v_add_f32_e32 v21, v15, v21
	v_add_f32_e32 v28, v21, v20
	v_mov_b32_e32 v20, v24
	v_mov_b32_e32 v21, v16
	v_mov_b32_e32 v22, v25
	v_mov_b32_e32 v23, v17
	v_pk_add_f32 v[20:21], v[20:21], v[22:23]
	v_mov_b32_e32 v22, v26
	v_mov_b32_e32 v23, v18
	v_pk_add_f32 v[20:21], v[22:23], v[20:21]
	v_mov_b32_e32 v22, v27
	v_mov_b32_e32 v23, v19
	v_pk_add_f32 v[20:21], v[22:23], v[20:21]
	v_mov_b32_e32 v22, v41
	v_add_f32_e32 v21, v21, v28
	v_add_f32_e32 v28, v20, v21
	v_mov_b32_e32 v20, v40
	v_mov_b32_e32 v21, v32
	v_mov_b32_e32 v23, v33
	v_pk_add_f32 v[20:21], v[20:21], v[22:23]
	v_mov_b32_e32 v22, v42
	v_mov_b32_e32 v23, v34
	v_pk_add_f32 v[20:21], v[22:23], v[20:21]
	v_mov_b32_e32 v22, v43
	v_mov_b32_e32 v23, v35
	v_pk_add_f32 v[20:21], v[22:23], v[20:21]
	s_mov_b32 s29, 0x800000
	v_add_f32_e32 v21, v21, v28
	v_add_f32_e32 v20, v20, v21
	ds_bpermute_b32 v21, v120, v20
	v_ashrrev_i32_e32 v111, 31, v110
	v_mov_b32_e32 v101, v65
	v_mov_b32_e32 v103, v65
	v_mov_b32_e32 v105, v65
	s_waitcnt lgkmcnt(0)
	v_add_f32_e32 v20, v20, v21
	ds_bpermute_b32 v21, v121, v20
	v_mov_b32_e32 v107, v65
	v_mov_b32_e32 v109, v65
	s_waitcnt lgkmcnt(0)
	v_add_f32_e32 v20, v20, v21
	ds_bpermute_b32 v21, v122, v20
	s_waitcnt lgkmcnt(0)
; __device__ __forceinline__ float wave_sum(float v) {
; #pragma unroll
;   for (int o = 32; o >= 1; o >>= 1) v += __shfl_xor(v, o);
;   return v;
; }
; __device__ __forceinline__ void ln_finish_row(int r, int lane, f32x4 (&x)[8], float* dstf, bf16_t* dstb, const float* g, const float* bta) {
;     ...
;   const float mean = wave_sum(sm) * (1.0f / 2048.0f);
;   float q = 0.f;
; #pragma unroll
;   for (int k = 0; k < 8; ++k) { x[k] = x[k] - mean; q += x[k][0] * x[k][0] + x[k][1] * x[k][1] + x[k][2] * x[k][2] + x[k][3] * x[k][3]; }
;   const float rstd = rsqrtf(wave_sum(q) * (1.0f / 2048.0f) + LN_EPS);
	v_add_f32_e32 v20, v20, v21
	ds_bpermute_b32 v21, v123, v20
	s_waitcnt lgkmcnt(0)
	v_add_f32_e32 v20, v20, v21
	ds_bpermute_b32 v21, v124, v20
	s_waitcnt lgkmcnt(0)
	v_add_f32_e32 v20, v20, v21
	ds_bpermute_b32 v21, v125, v20
	s_waitcnt lgkmcnt(0)
	v_add_f32_e32 v44, v20, v21
	v_fmamk_f32 v1, v44, 0xba000000, v1
	v_fmamk_f32 v5, v44, 0xba000000, v5
	v_fmac_f32_e32 v0, 0xba000000, v44
	v_mul_f32_e32 v20, v1, v1
	v_fmac_f32_e32 v4, 0xba000000, v44
	v_mul_f32_e32 v21, v5, v5
	v_fmamk_f32 v2, v44, 0xba000000, v2
	v_fmac_f32_e32 v20, v0, v0
	v_fmamk_f32 v6, v44, 0xba000000, v6
	v_fmac_f32_e32 v21, v4, v4
	v_fmamk_f32 v3, v44, 0xba000000, v3
	v_fmac_f32_e32 v20, v2, v2
	v_fmamk_f32 v7, v44, 0xba000000, v7
	v_fmac_f32_e32 v21, v6, v6
	v_fmac_f32_e32 v20, v3, v3
	v_fmac_f32_e32 v21, v7, v7
	v_fmamk_f32 v9, v44, 0xba000000, v9
	v_add_f32_e32 v20, v20, v21
	v_fmac_f32_e32 v8, 0xba000000, v44
	v_mul_f32_e32 v21, v9, v9
	v_fmamk_f32 v10, v44, 0xba000000, v10
	v_fmac_f32_e32 v21, v8, v8
	v_fmamk_f32 v11, v44, 0xba000000, v11
	v_fmac_f32_e32 v21, v10, v10
	v_fmac_f32_e32 v21, v11, v11
	v_fmamk_f32 v13, v44, 0xba000000, v13
	v_add_f32_e32 v20, v21, v20
	v_fmac_f32_e32 v12, 0xba000000, v44
	v_mul_f32_e32 v21, v13, v13
	v_fmamk_f32 v14, v44, 0xba000000, v14
	v_fmac_f32_e32 v21, v12, v12
	v_fmamk_f32 v15, v44, 0xba000000, v15
	v_fmac_f32_e32 v21, v14, v14
	v_fmamk_f32 v17, v44, 0xba000000, v17
	v_fmamk_f32 v25, v44, 0xba000000, v25
	v_fmac_f32_e32 v21, v15, v15
	v_fmac_f32_e32 v16, 0xba000000, v44
	v_fmac_f32_e32 v24, 0xba000000, v44
	v_mov_b32_e32 v22, v25
	v_mov_b32_e32 v23, v17
	v_add_f32_e32 v45, v21, v20
	v_mov_b32_e32 v20, v24
	v_mov_b32_e32 v21, v16
	v_pk_mul_f32 v[22:23], v[22:23], v[22:23]
	v_fmamk_f32 v18, v44, 0xba000000, v18
	v_pk_fma_f32 v[36:37], v[20:21], v[20:21], v[22:23]
	s_nop 1
	v_mov_b64_e32 v[20:21], v[160:161]
	v_mov_b64_e32 v[22:23], v[162:163]
	s_nop 1
	v_mov_b64_e32 v[28:29], v[164:165]
	v_mov_b64_e32 v[30:31], v[166:167]
	v_fmamk_f32 v26, v44, 0xba000000, v26
	v_fmamk_f32 v19, v44, 0xba000000, v19
	v_fmamk_f32 v27, v44, 0xba000000, v27
	v_mov_b32_e32 v38, v26
	v_mov_b32_e32 v39, v18
	v_pk_fma_f32 v[36:37], v[38:39], v[38:39], v[36:37]
	v_mov_b32_e32 v38, v27
	v_mov_b32_e32 v39, v19
	v_pk_fma_f32 v[36:37], v[38:39], v[38:39], v[36:37]
	v_fmamk_f32 v33, v44, 0xba000000, v33
	v_fmamk_f32 v41, v44, 0xba000000, v41
	v_add_f32_e32 v37, v37, v45
	v_fmac_f32_e32 v32, 0xba000000, v44
	v_fmac_f32_e32 v40, 0xba000000, v44
	v_mov_b32_e32 v38, v41
	v_mov_b32_e32 v39, v33
	v_add_f32_e32 v45, v36, v37
	v_fmamk_f32 v34, v44, 0xba000000, v34
	v_fmamk_f32 v42, v44, 0xba000000, v42
	v_mov_b32_e32 v36, v40
	v_mov_b32_e32 v37, v32
	v_pk_mul_f32 v[38:39], v[38:39], v[38:39]
	v_fmamk_f32 v35, v44, 0xba000000, v35
	v_fmamk_f32 v43, v44, 0xba000000, v43
	v_pk_fma_f32 v[36:37], v[36:37], v[36:37], v[38:39]
	v_mov_b32_e32 v38, v42
	v_mov_b32_e32 v39, v34
	v_pk_fma_f32 v[36:37], v[38:39], v[38:39], v[36:37]
	v_mov_b32_e32 v38, v43
	v_mov_b32_e32 v39, v35
	v_pk_fma_f32 v[36:37], v[38:39], v[38:39], v[36:37]
	v_lshlrev_b64 v[38:39], 13, v[110:111]
	v_add_f32_e32 v37, v37, v45
	v_add_f32_e32 v36, v36, v37
	ds_bpermute_b32 v37, v120, v36
	v_lshl_add_u64 v[38:39], s[22:23], 0, v[38:39]
	s_waitcnt lgkmcnt(0)
	v_add_f32_e32 v36, v36, v37
	ds_bpermute_b32 v37, v121, v36
	s_waitcnt lgkmcnt(0)
	v_add_f32_e32 v36, v36, v37
	ds_bpermute_b32 v37, v122, v36
	s_waitcnt lgkmcnt(0)
	v_add_f32_e32 v36, v36, v37
	ds_bpermute_b32 v37, v123, v36
	s_waitcnt lgkmcnt(0)
	v_add_f32_e32 v36, v36, v37
	ds_bpermute_b32 v37, v124, v36
	s_waitcnt lgkmcnt(0)
	v_add_f32_e32 v36, v36, v37
	ds_bpermute_b32 v37, v125, v36
	s_waitcnt lgkmcnt(0)
; __device__ __forceinline__ u32x2 pack4(f32x4 v) { u32x2 r; r[0] = cvt_pk(v[0], v[1]); r[1] = cvt_pk(v[2], v[3]); return r; }
; __device__ __forceinline__ void ln_finish_row(int r, int lane, f32x4 (&x)[8], float* dstf, bf16_t* dstb, const float* g, const float* bta) {
;     ...
;   for (int k = 0; k < 8; ++k) {
;     const int col = 256 * k + 4 * lane;
;     const f32x4 gg = *(const f32x4*)(g + col), bb = *(const f32x4*)(bta + col);
;     const f32x4 y = x[k] * rstd * gg + bb;
;     *(f32x4*)(dstf + (size_t)r * 2048 + col) = y;
;     if (dstb) *(u32x2*)(dstb + (size_t)r * 2048 + col) = pack4(y);
;   }
	v_add_f32_e32 v36, v36, v37
	v_fmamk_f32 v36, v36, 0x3a000000, v228
	v_mul_f32_e32 v37, 0x4b800000, v36
	v_cmp_gt_f32_e32 vcc, s29, v36
	s_nop 1
	v_cndmask_b32_e32 v36, v36, v37, vcc
	v_rsq_f32_e32 v36, v36
	s_nop 0
	v_mul_f32_e32 v37, 0x45800000, v36
	v_cndmask_b32_e32 v36, v36, v37, vcc
	v_pk_mul_f32 v[44:45], v[0:1], v[36:37] op_sel_hi:[1,0]
	v_pk_mul_f32 v[46:47], v[2:3], v[36:37] op_sel_hi:[1,0]
	v_pk_fma_f32 v[20:21], v[20:21], v[44:45], v[28:29]
	v_pk_fma_f32 v[22:23], v[22:23], v[46:47], v[30:31]
	v_lshl_add_u64 v[44:45], v[38:39], 0, v[100:101]
	global_store_dwordx4 v[44:45], v[20:23], off
	s_nop 1
	v_mov_b64_e32 v[20:21], v[170:171]
	v_mov_b64_e32 v[22:23], v[172:173]
	s_nop 0
	s_nop 1
	v_mov_b64_e32 v[28:29], v[174:175]
	v_mov_b64_e32 v[30:31], v[176:177]
	v_pk_mul_f32 v[46:47], v[6:7], v[36:37] op_sel_hi:[1,0]
	v_pk_mul_f32 v[48:49], v[4:5], v[36:37] op_sel_hi:[1,0]
	v_pk_fma_f32 v[22:23], v[22:23], v[46:47], v[30:31]
	v_pk_fma_f32 v[20:21], v[20:21], v[48:49], v[28:29]
	global_store_dwordx4 v[44:45], v[20:23], off offset:1024
	s_nop 1
	v_mov_b64_e32 v[20:21], v[178:179]
	v_mov_b64_e32 v[22:23], v[180:181]
	s_nop 0
	s_nop 1
	v_mov_b64_e32 v[28:29], v[182:183]
	v_mov_b64_e32 v[30:31], v[184:185]
	v_pk_mul_f32 v[46:47], v[10:11], v[36:37] op_sel_hi:[1,0]
	v_pk_mul_f32 v[48:49], v[8:9], v[36:37] op_sel_hi:[1,0]
	v_pk_fma_f32 v[22:23], v[22:23], v[46:47], v[30:31]
	v_pk_fma_f32 v[20:21], v[20:21], v[48:49], v[28:29]
	global_store_dwordx4 v[44:45], v[20:23], off offset:2048
	s_nop 1
	v_mov_b64_e32 v[20:21], v[188:189]
	v_mov_b64_e32 v[22:23], v[190:191]
	s_nop 0
	s_nop 1
	v_mov_b64_e32 v[28:29], v[192:193]
	v_mov_b64_e32 v[30:31], v[194:195]
	v_pk_mul_f32 v[46:47], v[14:15], v[36:37] op_sel_hi:[1,0]
	v_pk_mul_f32 v[48:49], v[12:13], v[36:37] op_sel_hi:[1,0]
	v_pk_fma_f32 v[22:23], v[22:23], v[46:47], v[30:31]
	v_pk_fma_f32 v[20:21], v[20:21], v[48:49], v[28:29]
	global_store_dwordx4 v[44:45], v[20:23], off offset:3072
	s_nop 1
	v_mov_b64_e32 v[20:21], v[196:197]
	v_mov_b64_e32 v[22:23], v[198:199]
	s_nop 0
	s_nop 1
	v_mov_b64_e32 v[28:29], v[200:201]
	v_mov_b64_e32 v[30:31], v[202:203]
	v_pk_mul_f32 v[46:47], v[18:19], v[36:37] op_sel_hi:[1,0]
	v_pk_mul_f32 v[48:49], v[16:17], v[36:37] op_sel_hi:[1,0]
	v_lshl_add_u64 v[44:45], v[38:39], 0, v[102:103]
	v_pk_fma_f32 v[20:21], v[20:21], v[48:49], v[28:29]
	v_pk_fma_f32 v[22:23], v[22:23], v[46:47], v[30:31]
	global_store_dwordx4 v[44:45], v[20:23], off
	s_nop 1
	v_mov_b64_e32 v[20:21], v[204:205]
	v_mov_b64_e32 v[22:23], v[206:207]
	s_nop 0
	s_nop 1
	v_mov_b64_e32 v[28:29], v[208:209]
	v_mov_b64_e32 v[30:31], v[210:211]
	v_pk_mul_f32 v[46:47], v[26:27], v[36:37] op_sel_hi:[1,0]
	v_pk_mul_f32 v[48:49], v[24:25], v[36:37] op_sel_hi:[1,0]
	v_lshl_add_u64 v[44:45], v[38:39], 0, v[104:105]
	v_pk_fma_f32 v[20:21], v[20:21], v[48:49], v[28:29]
	v_pk_fma_f32 v[22:23], v[22:23], v[46:47], v[30:31]
	global_store_dwordx4 v[44:45], v[20:23], off
	s_nop 1
	v_mov_b64_e32 v[20:21], v[212:213]
	v_mov_b64_e32 v[22:23], v[214:215]
	s_nop 0
	s_nop 1
	v_mov_b64_e32 v[28:29], v[216:217]
	v_mov_b64_e32 v[30:31], v[218:219]
	v_pk_mul_f32 v[46:47], v[34:35], v[36:37] op_sel_hi:[1,0]
	v_pk_mul_f32 v[48:49], v[32:33], v[36:37] op_sel_hi:[1,0]
	v_lshl_add_u64 v[44:45], v[38:39], 0, v[106:107]
	v_pk_fma_f32 v[20:21], v[20:21], v[48:49], v[28:29]
	v_pk_fma_f32 v[22:23], v[22:23], v[46:47], v[30:31]
	global_store_dwordx4 v[44:45], v[20:23], off
	s_nop 1
	v_mov_b64_e32 v[20:21], v[220:221]
	v_mov_b64_e32 v[22:23], v[222:223]
	s_nop 0
	s_nop 1
	v_mov_b64_e32 v[28:29], v[238:239]
	v_mov_b64_e32 v[30:31], v[240:241]
	v_pk_mul_f32 v[44:45], v[42:43], v[36:37] op_sel_hi:[1,0]
	v_pk_mul_f32 v[36:37], v[40:41], v[36:37] op_sel_hi:[1,0]
	v_pk_fma_f32 v[22:23], v[22:23], v[44:45], v[30:31]
	v_pk_fma_f32 v[20:21], v[20:21], v[36:37], v[28:29]
	v_lshl_add_u64 v[28:29], v[38:39], 0, v[108:109]
	global_store_dwordx4 v[28:29], v[20:23], off
	s_branch .LBB0_1494
